# FFN-in K-loop: MFMAs reordered so that each accumulator's two K-half MFMAs issue back to back (accumulate chain), same per-accumulator order
# speedup vs baseline: 1.0065x; 1.0065x over previous
; #define PG8_STAGE(bufoff, gbase, voff) do { _Pragma("unroll") for (int _i = 0; _i < 2; ++_i) \
;         __builtin_amdgcn_global_load_lds((const unsigned*)((const char*)(gbase) + (voff)[_i]), (PG8_LAS unsigned*)(lds + (bufoff) + ldsw + _i * 8192), 16, 0, 0); } while (0)
; #define PG8_LDA(dst, b, h) do { _Pragma("unroll") for (int m = 0; m < 4; ++m) _Pragma("unroll") for (int k = 0; k < 2; ++k) dst[m][k] = *(const PG8_LAS bf16x8*)(lds + PG8_SA(b, h) + aoff + m * 2048 + k * 1024); } while (0)
; #define PG8_LDB(dst, b, h) do { _Pragma("unroll") for (int n = 0; n < 2; ++n) _Pragma("unroll") for (int k = 0; k < 2; ++k) dst[n][k] = *(const PG8_LAS bf16x8*)(lds + PG8_SB(b, h) + boff + n * 2048 + k * 1024); } while (0)
; #define PG8_MMA(ai, bj, At, Bt) do { __builtin_amdgcn_s_setprio(1); _Pragma("unroll") for (int m = 0; m < 4; ++m) _Pragma("unroll") for (int n = 0; n < 2; ++n) _Pragma("unroll") for (int k = 0; k < 2; ++k) \
;         acc[ai][bj][m][n] = __builtin_amdgcn_mfma_f32_16x16x32_bf16(Bt[n][k], At[m][k], acc[ai][bj][m][n], 0, 0, 0); __builtin_amdgcn_s_setprio(0); } while (0)
; #define PG8_WAIT_V(n) asm volatile("s_waitcnt vmcnt(" #n ")" ::: "memory")
; #define PG8_WAIT_L(n) asm volatile("s_waitcnt lgkmcnt(" #n ")" ::: "memory")
; #define PG8_BAR __builtin_amdgcn_s_barrier()
; #define PG8_SCHED __builtin_amdgcn_sched_barrier(0)
; template <class Epi, class Sched, bool ALIGN_EPI = false, bool SP2 = false>
; __device__ __forceinline__ void gemm_phase(PG8_LAS unsigned char* lds, const Gemm g, const Sched& S, const Epi& E) {
;     ...
;             PG8_LDB(B0, 0, 0); PG8_LDB(B1, 0, 1); PG8_SCHED; PG8_LDA(At, 0, 0); PG8_STAGE(PG8_SA(1, 1), a1 + hstep, voffA);
;             PG8_WAIT_V(8); PG8_WAIT_L(0); PG8_BAR; PG8_MMA(0, 0, At, B0); PG8_MMA(0, 1, At, B1); PG8_BAR; PG8_SCHED;
;             PG8_LDA(At, 0, 1); PG8_STAGE(PG8_SB(0, 0), b2, voffB); PG8_STAGE(PG8_SB(0, 1), b2 + hstep, voffB); PG8_STAGE(PG8_SA(0, 0), a2, voffA);
;             PG8_WAIT_V(8); PG8_WAIT_L(0); PG8_BAR; PG8_MMA(1, 0, At, B0); PG8_MMA(1, 1, At, B1); PG8_BAR; PG8_SCHED;
.LBB11_456:
	s_add_u32 s18, s16, 0xfff80080
	s_addc_u32 s19, s17, -1
	s_add_i32 s49, 0, 0x10000
	s_cmp_eq_u32 s48, 28
	s_cselect_b32 s21, s11, s19
	s_cselect_b32 s20, s44, s18
	v_add_u32_e32 v144, s49, v147
	s_cselect_b32 s19, s9, s47
	s_cselect_b32 s18, s45, s46
	s_add_i32 s52, 0, 0x14000
	ds_read_b128 v[150:153], v144
	ds_read_b128 v[154:157], v144 offset:1024
	ds_read_b128 v[158:161], v144 offset:2048
	ds_read_b128 v[162:165], v144 offset:3072
	v_add_u32_e32 v144, s52, v147
	ds_read_b128 v[166:169], v144
	ds_read_b128 v[170:173], v144 offset:1024
	ds_read_b128 v[174:177], v144 offset:2048
	ds_read_b128 v[178:181], v144 offset:3072
	v_lshl_add_u64 v[144:145], s[16:17], 0, v[140:141]
	s_add_i32 m0, s29, 0xc000
	ds_read_b128 v[198:201], v149
	ds_read_b128 v[202:205], v149 offset:1024
	ds_read_b128 v[220:223], v149 offset:2048
	ds_read_b128 v[224:227], v149 offset:3072
	ds_read_b128 v[228:231], v149 offset:4096
	ds_read_b128 v[232:235], v149 offset:5120
	ds_read_b128 v[236:239], v149 offset:6144
	ds_read_b128 v[240:243], v149 offset:7168
	global_load_lds_dwordx4 v[144:145], off
	v_lshl_add_u64 v[144:145], s[16:17], 0, v[142:143]
	s_add_i32 m0, s29, 0xe000
	s_nop 0
	global_load_lds_dwordx4 v[144:145], off
	s_waitcnt vmcnt(8)
	s_waitcnt lgkmcnt(0)
	s_barrier
	s_setprio 1
	s_waitcnt lgkmcnt(0)
	v_mfma_f32_16x16x32_bf16 v[124:127], v[150:153], v[198:201], v[124:127]
	v_mfma_f32_16x16x32_bf16 v[124:127], v[154:157], v[202:205], v[124:127]
	v_mfma_f32_16x16x32_bf16 v[116:119], v[158:161], v[198:201], v[116:119]
	v_mfma_f32_16x16x32_bf16 v[116:119], v[162:165], v[202:205], v[116:119]
	v_mfma_f32_16x16x32_bf16 v[108:111], v[150:153], v[220:223], v[108:111]
	v_mfma_f32_16x16x32_bf16 v[108:111], v[154:157], v[224:227], v[108:111]
	v_mfma_f32_16x16x32_bf16 v[100:103], v[158:161], v[220:223], v[100:103]
	v_mfma_f32_16x16x32_bf16 v[100:103], v[162:165], v[224:227], v[100:103]
	v_mfma_f32_16x16x32_bf16 v[92:95], v[150:153], v[228:231], v[92:95]
	v_mfma_f32_16x16x32_bf16 v[92:95], v[154:157], v[232:235], v[92:95]
	v_mfma_f32_16x16x32_bf16 v[84:87], v[158:161], v[228:231], v[84:87]
	v_mfma_f32_16x16x32_bf16 v[84:87], v[162:165], v[232:235], v[84:87]
	v_mfma_f32_16x16x32_bf16 v[76:79], v[150:153], v[236:239], v[76:79]
	v_mfma_f32_16x16x32_bf16 v[76:79], v[154:157], v[240:243], v[76:79]
	v_mfma_f32_16x16x32_bf16 v[68:71], v[158:161], v[236:239], v[68:71]
	v_mfma_f32_16x16x32_bf16 v[68:71], v[162:165], v[240:243], v[68:71]
	s_setprio 0
	s_setprio 1
	v_mfma_f32_16x16x32_bf16 v[128:131], v[166:169], v[198:201], v[128:131]
	v_mfma_f32_16x16x32_bf16 v[128:131], v[170:173], v[202:205], v[128:131]
	v_mfma_f32_16x16x32_bf16 v[120:123], v[174:177], v[198:201], v[120:123]
	v_mfma_f32_16x16x32_bf16 v[120:123], v[178:181], v[202:205], v[120:123]
	v_mfma_f32_16x16x32_bf16 v[112:115], v[166:169], v[220:223], v[112:115]
	v_mfma_f32_16x16x32_bf16 v[112:115], v[170:173], v[224:227], v[112:115]
	v_mfma_f32_16x16x32_bf16 v[104:107], v[174:177], v[220:223], v[104:107]
	v_mfma_f32_16x16x32_bf16 v[104:107], v[178:181], v[224:227], v[104:107]
	v_mfma_f32_16x16x32_bf16 v[96:99], v[166:169], v[228:231], v[96:99]
	v_mfma_f32_16x16x32_bf16 v[96:99], v[170:173], v[232:235], v[96:99]
	v_mfma_f32_16x16x32_bf16 v[88:91], v[174:177], v[228:231], v[88:91]
	v_mfma_f32_16x16x32_bf16 v[88:91], v[178:181], v[232:235], v[88:91]
	v_mfma_f32_16x16x32_bf16 v[80:83], v[166:169], v[236:239], v[80:83]
	v_mfma_f32_16x16x32_bf16 v[80:83], v[170:173], v[240:243], v[80:83]
	v_mfma_f32_16x16x32_bf16 v[72:75], v[174:177], v[236:239], v[72:75]
	v_mfma_f32_16x16x32_bf16 v[72:75], v[178:181], v[240:243], v[72:75]
	s_setprio 0
	s_barrier
	s_add_i32 s49, s49, s27
	v_lshl_add_u64 v[144:145], s[18:19], 0, v[2:3]
	s_mov_b32 m0, s49
	ds_read_b128 v[198:201], v149 offset:16384
	ds_read_b128 v[202:205], v149 offset:17408
	ds_read_b128 v[220:223], v149 offset:18432
	ds_read_b128 v[224:227], v149 offset:19456
	ds_read_b128 v[228:231], v149 offset:20480
	ds_read_b128 v[232:235], v149 offset:21504
	ds_read_b128 v[236:239], v149 offset:22528
	ds_read_b128 v[240:243], v149 offset:23552
	global_load_lds_dwordx4 v[144:145], off
	s_add_i32 m0, s49, 0x2000
	s_add_u32 s50, s18, 0x80000
	v_lshl_add_u64 v[206:207], s[18:19], 0, v[132:133]
	s_addc_u32 s51, s19, 0
	s_add_i32 s49, s52, s27
	global_load_lds_dwordx4 v[206:207], off
	v_lshl_add_u64 v[244:245], s[50:51], 0, v[2:3]
	s_mov_b32 m0, s49
	v_lshl_add_u64 v[246:247], s[20:21], 0, v[134:135]
	global_load_lds_dwordx4 v[244:245], off
	v_lshl_add_u64 v[244:245], s[50:51], 0, v[132:133]
	s_add_i32 m0, s49, 0x2000
	s_nop 0
	global_load_lds_dwordx4 v[244:245], off
	v_lshl_add_u64 v[244:245], s[20:21], 0, v[136:137]
	s_mov_b32 m0, s29
	s_nop 0
	global_load_lds_dwordx4 v[244:245], off
	s_mov_b32 m0, s30
	s_nop 0
	global_load_lds_dwordx4 v[246:247], off
	s_waitcnt vmcnt(8)
	s_waitcnt lgkmcnt(0)
	s_barrier
; #define PG8_STAGE(bufoff, gbase, voff) do { _Pragma("unroll") for (int _i = 0; _i < 2; ++_i) \
;         __builtin_amdgcn_global_load_lds((const unsigned*)((const char*)(gbase) + (voff)[_i]), (PG8_LAS unsigned*)(lds + (bufoff) + ldsw + _i * 8192), 16, 0, 0); } while (0)
; #define PG8_LDA(dst, b, h) do { _Pragma("unroll") for (int m = 0; m < 4; ++m) _Pragma("unroll") for (int k = 0; k < 2; ++k) dst[m][k] = *(const PG8_LAS bf16x8*)(lds + PG8_SA(b, h) + aoff + m * 2048 + k * 1024); } while (0)
; #define PG8_LDB(dst, b, h) do { _Pragma("unroll") for (int n = 0; n < 2; ++n) _Pragma("unroll") for (int k = 0; k < 2; ++k) dst[n][k] = *(const PG8_LAS bf16x8*)(lds + PG8_SB(b, h) + boff + n * 2048 + k * 1024); } while (0)
; #define PG8_MMA(ai, bj, At, Bt) do { __builtin_amdgcn_s_setprio(1); _Pragma("unroll") for (int m = 0; m < 4; ++m) _Pragma("unroll") for (int n = 0; n < 2; ++n) _Pragma("unroll") for (int k = 0; k < 2; ++k) \
;         acc[ai][bj][m][n] = __builtin_amdgcn_mfma_f32_16x16x32_bf16(Bt[n][k], At[m][k], acc[ai][bj][m][n], 0, 0, 0); __builtin_amdgcn_s_setprio(0); } while (0)
; #define PG8_WAIT_V(n) asm volatile("s_waitcnt vmcnt(" #n ")" ::: "memory")
; #define PG8_WAIT_L(n) asm volatile("s_waitcnt lgkmcnt(" #n ")" ::: "memory")
; #define PG8_BAR __builtin_amdgcn_s_barrier()
; #define PG8_SCHED __builtin_amdgcn_sched_barrier(0)
; template <class Epi, class Sched, bool ALIGN_EPI = false, bool SP2 = false>
; __device__ __forceinline__ void gemm_phase(PG8_LAS unsigned char* lds, const Gemm g, const Sched& S, const Epi& E) {
;     ...
;             PG8_WAIT_V(8); PG8_WAIT_L(0); PG8_BAR; PG8_MMA(0, 0, At, B0); PG8_MMA(0, 1, At, B1); PG8_BAR; PG8_SCHED;
;             PG8_LDA(At, 0, 1); PG8_STAGE(PG8_SB(0, 0), b2, voffB); PG8_STAGE(PG8_SB(0, 1), b2 + hstep, voffB); PG8_STAGE(PG8_SA(0, 0), a2, voffA);
;             PG8_WAIT_V(8); PG8_WAIT_L(0); PG8_BAR; PG8_MMA(1, 0, At, B0); PG8_MMA(1, 1, At, B1); PG8_BAR; PG8_SCHED;
;             PG8_LDB(B0, 1, 0); PG8_LDB(B1, 1, 1); PG8_SCHED; PG8_LDA(At, 1, 0); PG8_STAGE(PG8_SA(0, 1), a2 + hstep, voffA);
;             PG8_WAIT_V(8); PG8_WAIT_L(0); PG8_BAR; PG8_MMA(0, 0, At, B0); PG8_MMA(0, 1, At, B1); PG8_BAR; PG8_SCHED;
	s_setprio 1
	s_waitcnt lgkmcnt(0)
	v_mfma_f32_16x16x32_bf16 v[60:63], v[150:153], v[198:201], v[60:63]
	v_mfma_f32_16x16x32_bf16 v[60:63], v[154:157], v[202:205], v[60:63]
	v_mfma_f32_16x16x32_bf16 v[52:55], v[158:161], v[198:201], v[52:55]
	v_mfma_f32_16x16x32_bf16 v[52:55], v[162:165], v[202:205], v[52:55]
	v_mfma_f32_16x16x32_bf16 v[44:47], v[150:153], v[220:223], v[44:47]
	v_mfma_f32_16x16x32_bf16 v[44:47], v[154:157], v[224:227], v[44:47]
	v_mfma_f32_16x16x32_bf16 v[36:39], v[158:161], v[220:223], v[36:39]
	v_mfma_f32_16x16x32_bf16 v[36:39], v[162:165], v[224:227], v[36:39]
	v_mfma_f32_16x16x32_bf16 v[28:31], v[150:153], v[228:231], v[28:31]
	v_mfma_f32_16x16x32_bf16 v[28:31], v[154:157], v[232:235], v[28:31]
	v_mfma_f32_16x16x32_bf16 v[20:23], v[158:161], v[228:231], v[20:23]
	v_mfma_f32_16x16x32_bf16 v[20:23], v[162:165], v[232:235], v[20:23]
	v_mfma_f32_16x16x32_bf16 v[12:15], v[150:153], v[236:239], v[12:15]
	v_mfma_f32_16x16x32_bf16 v[12:15], v[154:157], v[240:243], v[12:15]
	v_mfma_f32_16x16x32_bf16 v[4:7], v[158:161], v[236:239], v[4:7]
	v_mfma_f32_16x16x32_bf16 v[4:7], v[162:165], v[240:243], v[4:7]
	s_setprio 0
	s_setprio 1
	v_mfma_f32_16x16x32_bf16 v[64:67], v[166:169], v[198:201], v[64:67]
	v_mfma_f32_16x16x32_bf16 v[64:67], v[170:173], v[202:205], v[64:67]
	v_mfma_f32_16x16x32_bf16 v[56:59], v[174:177], v[198:201], v[56:59]
	v_mfma_f32_16x16x32_bf16 v[56:59], v[178:181], v[202:205], v[56:59]
	v_mfma_f32_16x16x32_bf16 v[48:51], v[166:169], v[220:223], v[48:51]
	v_mfma_f32_16x16x32_bf16 v[48:51], v[170:173], v[224:227], v[48:51]
	v_mfma_f32_16x16x32_bf16 v[40:43], v[174:177], v[220:223], v[40:43]
	v_mfma_f32_16x16x32_bf16 v[40:43], v[178:181], v[224:227], v[40:43]
	v_mfma_f32_16x16x32_bf16 v[32:35], v[166:169], v[228:231], v[32:35]
	v_mfma_f32_16x16x32_bf16 v[32:35], v[170:173], v[232:235], v[32:35]
	v_mfma_f32_16x16x32_bf16 v[24:27], v[174:177], v[228:231], v[24:27]
	v_mfma_f32_16x16x32_bf16 v[24:27], v[178:181], v[232:235], v[24:27]
	v_mfma_f32_16x16x32_bf16 v[16:19], v[166:169], v[236:239], v[16:19]
	v_mfma_f32_16x16x32_bf16 v[16:19], v[170:173], v[240:243], v[16:19]
	v_mfma_f32_16x16x32_bf16 v[8:11], v[174:177], v[236:239], v[8:11]
	v_mfma_f32_16x16x32_bf16 v[8:11], v[178:181], v[240:243], v[8:11]
	s_setprio 0
	s_barrier
	s_add_i32 s49, 0, 0x18000
	s_add_i32 s50, 0, 0x1c000
	v_add_u32_e32 v162, s49, v147
	v_add_u32_e32 v178, s50, v147
	ds_read_b128 v[150:153], v162
	ds_read_b128 v[154:157], v162 offset:1024
	ds_read_b128 v[158:161], v162 offset:2048
	ds_read_b128 v[162:165], v162 offset:3072
	ds_read_b128 v[166:169], v178
	ds_read_b128 v[170:173], v178 offset:1024
	ds_read_b128 v[174:177], v178 offset:2048
	ds_read_b128 v[178:181], v178 offset:3072
	s_add_u32 s20, s20, 0x80000
	s_addc_u32 s21, s21, 0
	s_mov_b32 m0, s33
	v_lshl_add_u64 v[196:197], s[20:21], 0, v[136:137]
	ds_read_b128 v[198:201], v149 offset:32768
	ds_read_b128 v[202:205], v149 offset:33792
	ds_read_b128 v[220:223], v149 offset:34816
	ds_read_b128 v[224:227], v149 offset:35840
	ds_read_b128 v[228:231], v149 offset:36864
	ds_read_b128 v[232:235], v149 offset:37888
	ds_read_b128 v[236:239], v149 offset:38912
	ds_read_b128 v[240:243], v149 offset:39936
	global_load_lds_dwordx4 v[196:197], off
	v_lshl_add_u64 v[196:197], s[20:21], 0, v[134:135]
	s_mov_b32 m0, s38
	s_nop 0
	global_load_lds_dwordx4 v[196:197], off
	s_waitcnt vmcnt(8)
	s_waitcnt lgkmcnt(0)
	s_barrier
	s_setprio 1
	s_waitcnt lgkmcnt(0)
	v_mfma_f32_16x16x32_bf16 v[124:127], v[150:153], v[198:201], v[124:127]
	v_mfma_f32_16x16x32_bf16 v[124:127], v[154:157], v[202:205], v[124:127]
	v_mfma_f32_16x16x32_bf16 v[116:119], v[158:161], v[198:201], v[116:119]
	v_mfma_f32_16x16x32_bf16 v[116:119], v[162:165], v[202:205], v[116:119]
	v_mfma_f32_16x16x32_bf16 v[108:111], v[150:153], v[220:223], v[108:111]
	v_mfma_f32_16x16x32_bf16 v[108:111], v[154:157], v[224:227], v[108:111]
	v_mfma_f32_16x16x32_bf16 v[100:103], v[158:161], v[220:223], v[100:103]
	v_mfma_f32_16x16x32_bf16 v[100:103], v[162:165], v[224:227], v[100:103]
	v_mfma_f32_16x16x32_bf16 v[92:95], v[150:153], v[228:231], v[92:95]
	v_mfma_f32_16x16x32_bf16 v[92:95], v[154:157], v[232:235], v[92:95]
	v_mfma_f32_16x16x32_bf16 v[84:87], v[158:161], v[228:231], v[84:87]
	v_mfma_f32_16x16x32_bf16 v[84:87], v[162:165], v[232:235], v[84:87]
	v_mfma_f32_16x16x32_bf16 v[76:79], v[150:153], v[236:239], v[76:79]
	v_mfma_f32_16x16x32_bf16 v[76:79], v[154:157], v[240:243], v[76:79]
	v_mfma_f32_16x16x32_bf16 v[68:71], v[158:161], v[236:239], v[68:71]
	v_mfma_f32_16x16x32_bf16 v[68:71], v[162:165], v[240:243], v[68:71]
	s_setprio 0
	s_setprio 1
	v_mfma_f32_16x16x32_bf16 v[128:131], v[166:169], v[198:201], v[128:131]
	v_mfma_f32_16x16x32_bf16 v[128:131], v[170:173], v[202:205], v[128:131]
	v_mfma_f32_16x16x32_bf16 v[120:123], v[174:177], v[198:201], v[120:123]
	v_mfma_f32_16x16x32_bf16 v[120:123], v[178:181], v[202:205], v[120:123]
	v_mfma_f32_16x16x32_bf16 v[112:115], v[166:169], v[220:223], v[112:115]
	v_mfma_f32_16x16x32_bf16 v[112:115], v[170:173], v[224:227], v[112:115]
	v_mfma_f32_16x16x32_bf16 v[104:107], v[174:177], v[220:223], v[104:107]
	v_mfma_f32_16x16x32_bf16 v[104:107], v[178:181], v[224:227], v[104:107]
	v_mfma_f32_16x16x32_bf16 v[96:99], v[166:169], v[228:231], v[96:99]
	v_mfma_f32_16x16x32_bf16 v[96:99], v[170:173], v[232:235], v[96:99]
	v_mfma_f32_16x16x32_bf16 v[88:91], v[174:177], v[228:231], v[88:91]
	v_mfma_f32_16x16x32_bf16 v[88:91], v[178:181], v[232:235], v[88:91]
	v_mfma_f32_16x16x32_bf16 v[80:83], v[166:169], v[236:239], v[80:83]
	v_mfma_f32_16x16x32_bf16 v[80:83], v[170:173], v[240:243], v[80:83]
	v_mfma_f32_16x16x32_bf16 v[72:75], v[174:177], v[236:239], v[72:75]
	v_mfma_f32_16x16x32_bf16 v[72:75], v[178:181], v[240:243], v[72:75]
	s_setprio 0
	s_barrier
; #define PG8_STAGE(bufoff, gbase, voff) do { _Pragma("unroll") for (int _i = 0; _i < 2; ++_i) \
;         __builtin_amdgcn_global_load_lds((const unsigned*)((const char*)(gbase) + (voff)[_i]), (PG8_LAS unsigned*)(lds + (bufoff) + ldsw + _i * 8192), 16, 0, 0); } while (0)
; #define PG8_LDA(dst, b, h) do { _Pragma("unroll") for (int m = 0; m < 4; ++m) _Pragma("unroll") for (int k = 0; k < 2; ++k) dst[m][k] = *(const PG8_LAS bf16x8*)(lds + PG8_SA(b, h) + aoff + m * 2048 + k * 1024); } while (0)
; #define PG8_MMA(ai, bj, At, Bt) do { __builtin_amdgcn_s_setprio(1); _Pragma("unroll") for (int m = 0; m < 4; ++m) _Pragma("unroll") for (int n = 0; n < 2; ++n) _Pragma("unroll") for (int k = 0; k < 2; ++k) \
;         acc[ai][bj][m][n] = __builtin_amdgcn_mfma_f32_16x16x32_bf16(Bt[n][k], At[m][k], acc[ai][bj][m][n], 0, 0, 0); __builtin_amdgcn_s_setprio(0); } while (0)
; #define PG8_WAIT_V(n) asm volatile("s_waitcnt vmcnt(" #n ")" ::: "memory")
; #define PG8_WAIT_L(n) asm volatile("s_waitcnt lgkmcnt(" #n ")" ::: "memory")
; #define PG8_BAR __builtin_amdgcn_s_barrier()
; #define PG8_SCHED __builtin_amdgcn_sched_barrier(0)
; template <class Epi, class Sched, bool ALIGN_EPI = false, bool SP2 = false>
; __device__ __forceinline__ void gemm_phase(PG8_LAS unsigned char* lds, const Gemm g, const Sched& S, const Epi& E) {
;     ...
;         for (int t = 0; t < nt; t += 2) {
;     ...
;             PG8_LDA(At, 1, 1); PG8_STAGE(PG8_SB(1, 0), b3, voffB); PG8_STAGE(PG8_SB(1, 1), b3 + hstep, voffB); PG8_STAGE(PG8_SA(1, 0), a3, voffA);
;             PG8_WAIT_V(8); PG8_WAIT_L(0); PG8_BAR; PG8_MMA(1, 0, At, B0); PG8_MMA(1, 1, At, B1); PG8_BAR; PG8_SCHED;
	s_add_i32 s20, s49, s27
	v_lshl_add_u64 v[144:145], v[144:145], 0, s[34:35]
	s_mov_b32 m0, s20
	ds_read_b128 v[198:201], v149 offset:49152
	ds_read_b128 v[202:205], v149 offset:50176
	ds_read_b128 v[220:223], v149 offset:51200
	ds_read_b128 v[224:227], v149 offset:52224
	ds_read_b128 v[228:231], v149 offset:53248
	ds_read_b128 v[232:235], v149 offset:54272
	ds_read_b128 v[236:239], v149 offset:55296
	ds_read_b128 v[240:243], v149 offset:56320
	global_load_lds_dwordx4 v[144:145], off
	s_add_i32 m0, s20, 0x2000
	s_add_u32 s18, s18, 0x80080
	v_lshl_add_u64 v[144:145], v[206:207], 0, s[34:35]
	s_addc_u32 s19, s19, 0
	s_add_i32 s20, s50, s27
	global_load_lds_dwordx4 v[144:145], off
	v_lshl_add_u64 v[144:145], s[18:19], 0, v[2:3]
	s_mov_b32 m0, s20
	s_nop 0
	global_load_lds_dwordx4 v[144:145], off
	v_lshl_add_u64 v[144:145], s[18:19], 0, v[132:133]
	s_add_i32 m0, s20, 0x2000
	s_nop 0
	global_load_lds_dwordx4 v[144:145], off
	v_lshl_add_u64 v[144:145], v[244:245], 0, s[34:35]
	s_mov_b32 m0, s39
	s_nop 0
	global_load_lds_dwordx4 v[144:145], off
	v_lshl_add_u64 v[144:145], v[246:247], 0, s[34:35]
	s_mov_b32 m0, s40
	s_nop 0
	global_load_lds_dwordx4 v[144:145], off
	s_waitcnt vmcnt(8)
	s_waitcnt lgkmcnt(0)
	s_barrier
	s_setprio 1
	s_waitcnt lgkmcnt(0)
	v_mfma_f32_16x16x32_bf16 v[60:63], v[150:153], v[198:201], v[60:63]
	v_mfma_f32_16x16x32_bf16 v[60:63], v[154:157], v[202:205], v[60:63]
	v_mfma_f32_16x16x32_bf16 v[52:55], v[158:161], v[198:201], v[52:55]
	v_mfma_f32_16x16x32_bf16 v[52:55], v[162:165], v[202:205], v[52:55]
	v_mfma_f32_16x16x32_bf16 v[44:47], v[150:153], v[220:223], v[44:47]
	v_mfma_f32_16x16x32_bf16 v[44:47], v[154:157], v[224:227], v[44:47]
	v_mfma_f32_16x16x32_bf16 v[36:39], v[158:161], v[220:223], v[36:39]
	v_mfma_f32_16x16x32_bf16 v[36:39], v[162:165], v[224:227], v[36:39]
	v_mfma_f32_16x16x32_bf16 v[28:31], v[150:153], v[228:231], v[28:31]
	v_mfma_f32_16x16x32_bf16 v[28:31], v[154:157], v[232:235], v[28:31]
	v_mfma_f32_16x16x32_bf16 v[20:23], v[158:161], v[228:231], v[20:23]
	v_mfma_f32_16x16x32_bf16 v[20:23], v[162:165], v[232:235], v[20:23]
	v_mfma_f32_16x16x32_bf16 v[12:15], v[150:153], v[236:239], v[12:15]
	v_mfma_f32_16x16x32_bf16 v[12:15], v[154:157], v[240:243], v[12:15]
	v_mfma_f32_16x16x32_bf16 v[4:7], v[158:161], v[236:239], v[4:7]
	v_mfma_f32_16x16x32_bf16 v[4:7], v[162:165], v[240:243], v[4:7]
	s_setprio 0
	s_setprio 1
	v_mfma_f32_16x16x32_bf16 v[64:67], v[166:169], v[198:201], v[64:67]
	v_mfma_f32_16x16x32_bf16 v[64:67], v[170:173], v[202:205], v[64:67]
	v_mfma_f32_16x16x32_bf16 v[56:59], v[174:177], v[198:201], v[56:59]
	v_mfma_f32_16x16x32_bf16 v[56:59], v[178:181], v[202:205], v[56:59]
	v_mfma_f32_16x16x32_bf16 v[48:51], v[166:169], v[220:223], v[48:51]
	v_mfma_f32_16x16x32_bf16 v[48:51], v[170:173], v[224:227], v[48:51]
	v_mfma_f32_16x16x32_bf16 v[40:43], v[174:177], v[220:223], v[40:43]
	v_mfma_f32_16x16x32_bf16 v[40:43], v[178:181], v[224:227], v[40:43]
	v_mfma_f32_16x16x32_bf16 v[32:35], v[166:169], v[228:231], v[32:35]
	v_mfma_f32_16x16x32_bf16 v[32:35], v[170:173], v[232:235], v[32:35]
	v_mfma_f32_16x16x32_bf16 v[24:27], v[174:177], v[228:231], v[24:27]
	v_mfma_f32_16x16x32_bf16 v[24:27], v[178:181], v[232:235], v[24:27]
	v_mfma_f32_16x16x32_bf16 v[16:19], v[166:169], v[236:239], v[16:19]
	v_mfma_f32_16x16x32_bf16 v[16:19], v[170:173], v[240:243], v[16:19]
	v_mfma_f32_16x16x32_bf16 v[8:11], v[174:177], v[236:239], v[8:11]
	v_mfma_f32_16x16x32_bf16 v[8:11], v[178:181], v[240:243], v[8:11]
	s_setprio 0
	s_barrier
	s_add_i32 s48, s48, 2
	s_add_u32 s16, s16, 0x100
	s_addc_u32 s17, s17, 0
	s_add_u32 s46, s46, 0x100
	s_addc_u32 s47, s47, 0
	s_cmp_gt_u32 s48, 29
	s_cbranch_scc0 .LBB11_456
	s_and_b64 vcc, exec, s[6:7]
	s_cbranch_vccz .LBB11_459
	s_barrier
